# diff-attention unit epilogue: sub-norm gain table staged once in spare LDS and read with ds_read_b128 instead of 32 serialized global loads
# speedup vs baseline: 1.0378x; 1.0040x over previous
; #define LAS __attribute__((address_space(3)))
; DI KArgs fresh_args() { KArgs p = (KArgs)__builtin_amdgcn_kernarg_segment_ptr(); asm volatile("" : "+s"(p)); return p; }
; template <bool DIFF>
; DI void phase(LAS unsigned char* lds, const Tensors& Tn) {
;     ...
;     if (DIFF) {
;         LAS unsigned* slot = (LAS unsigned*)(lds + LDS_BYTES - 64);
;         if (threadIdx.x == 0) slot[1] = 0u;
;         __syncthreads();
;         for (;;) {
;             const unsigned qi = slot[1];
;             if (qi >= 8u) break;
; __global__ void __launch_bounds__(512, 2) fwd_kernel(Args a_unused) {
;     ...
;     { int tl_ = threadIdx.x; asm volatile("" : "+v"(tl_)); const int ln = tl_ & 63;
;       KArgs ka = fresh_args(); const float* lq1 = ka->lq1; const float* lk1 = ka->lk1; const float* lq2 = ka->lq2; const float* lk2 = ka->lk2;
;       float s1 = lq1[ln] * lk1[ln] + lq1[64 + ln] * lk1[64 + ln];
;       float s2 = lq2[ln] * lk2[ln] + lq2[64 + ln] * lk2[64 + ln];
;       const float lam = __expf(wave_sum(s1, ln)) - __expf(wave_sum(s2, ln)) + LAMBDA_INIT;
;       att::Tensors Tn{DQKV, 6144, DQKV + 2048, 6144, DQKV + 4096, nullptr, YDIFF, ka->diff_norm_g, lam, CTL, CTL + 768};
.LBB0_533:
	s_or_b64 exec, exec, s[4:5]
	s_waitcnt lgkmcnt(0)
	v_mov_b32_e32 v0, v242
	s_mov_b64 s[4:5], s[90:91]
	s_barrier
	s_load_dwordx8 s[8:15], s[4:5], 0x40
	v_lshlrev_b32_e32 v0, 2, v0
	v_and_b32_e32 v1, 0xfc, v0
	s_waitcnt lgkmcnt(0)
	global_load_dword v2, v1, s[8:9]
	global_load_dword v3, v1, s[10:11]
	global_load_dword v4, v1, s[8:9] offset:256
	global_load_dword v5, v1, s[10:11] offset:256
	global_load_dword v6, v1, s[12:13] offset:256
	global_load_dword v7, v1, s[14:15] offset:256
	global_load_dword v8, v1, s[12:13]
	global_load_dword v9, v1, s[14:15]
	v_bfrev_b32_e32 v1, 0.5
	v_bitop3_b32 v10, v0, 4, v1 bitop3:0x6c
	s_movk_i32 s0, 0x80
	s_waitcnt vmcnt(4)
	v_mul_f32_e32 v4, v4, v5
	v_fmac_f32_e32 v4, v2, v3
	s_waitcnt vmcnt(2)
	v_mul_f32_e32 v5, v6, v7
	ds_bpermute_b32 v2, v10, v4
	s_waitcnt vmcnt(0)
	v_fmac_f32_e32 v5, v8, v9
	ds_bpermute_b32 v3, v10, v5
	v_bitop3_b32 v6, v0, 8, v1 bitop3:0x6c
	s_waitcnt lgkmcnt(1)
	v_add_f32_e32 v2, v4, v2
	ds_bpermute_b32 v4, v6, v2
	s_waitcnt lgkmcnt(1)
	v_add_f32_e32 v3, v5, v3
	ds_bpermute_b32 v5, v6, v3
	v_bitop3_b32 v6, v0, 16, v1 bitop3:0x6c
	s_waitcnt lgkmcnt(1)
	v_add_f32_e32 v2, v2, v4
	ds_bpermute_b32 v4, v6, v2
	s_waitcnt lgkmcnt(1)
	v_add_f32_e32 v3, v3, v5
	ds_bpermute_b32 v5, v6, v3
	v_bitop3_b32 v6, v0, 32, v1 bitop3:0x6c
	s_waitcnt lgkmcnt(1)
	v_add_f32_e32 v2, v2, v4
	ds_bpermute_b32 v4, v6, v2
	s_waitcnt lgkmcnt(1)
	v_add_f32_e32 v3, v3, v5
	ds_bpermute_b32 v5, v6, v3
	v_bitop3_b32 v6, v0, 64, v1 bitop3:0x6c
	s_waitcnt lgkmcnt(1)
	v_add_f32_e32 v2, v2, v4
	ds_bpermute_b32 v4, v6, v2
	s_waitcnt lgkmcnt(1)
	v_add_f32_e32 v3, v3, v5
	ds_bpermute_b32 v5, v6, v3
	v_bitop3_b32 v6, v0, s0, v1 bitop3:0x6c
	s_waitcnt lgkmcnt(1)
	v_add_f32_e32 v1, v2, v4
	s_waitcnt lgkmcnt(0)
	v_add_f32_e32 v0, v3, v5
	ds_bpermute_b32 v3, v6, v1
	ds_bpermute_b32 v2, v6, v0
	s_mov_b64 s[6:7], exec
	v_readlane_b32 s0, v255, 1
	v_readlane_b32 s1, v255, 2
	s_and_b64 s[0:1], s[6:7], s[0:1]
	s_mov_b64 exec, s[0:1]
	s_add_i32 s0, 0, 0x23fc4
	v_mov_b32_e32 v4, 0
	v_mov_b32_e32 v5, s0
	ds_write_b32 v5, v4
	s_or_b64 exec, exec, s[6:7]
	s_add_i32 s0, 0, 0x23fc4
	v_mov_b32_e32 v4, s0
	s_waitcnt lgkmcnt(0)
	s_barrier
	ds_read_b32 v4, v4
	v_writelane_b32 v255, s90, 12
	s_mov_b32 s9, 0
	s_waitcnt lgkmcnt(0)
	v_cmp_lt_u32_e32 vcc, 7, v4
	v_writelane_b32 v255, s91, 13
	v_writelane_b32 v255, s92, 14
	s_and_b64 vcc, exec, vcc
	v_readfirstlane_b32 s1, v4
	v_writelane_b32 v255, s93, 15
	v_writelane_b32 v255, s94, 16
	v_writelane_b32 v255, s96, 17
	s_nop 1
	v_writelane_b32 v255, s97, 18
	s_cbranch_vccnz .LBB0_828
	v_add_f32_e32 v1, v1, v3
	v_add_f32_e32 v0, v0, v2
	v_mul_f32_e32 v1, 0x3fb8aa3b, v1
	v_mul_f32_e32 v0, 0x3fb8aa3b, v0
	v_exp_f32_e32 v1, v1
	v_exp_f32_e32 v0, v0
	s_load_dwordx2 s[10:11], s[4:5], 0x60
	s_add_u32 s12, s36, 0x92b0c00
	s_addc_u32 s13, s37, 0
	v_sub_f32_e32 v0, v1, v0
	v_add_f32_e32 v196, 0x3e4ccccd, v0
	s_add_i32 s2, 0, 0x23fc0
	s_mov_b32 s52, 2.0
	s_mov_b32 s54, -2.0
	v_mov_b32_e32 v197, v196
	v_mov_b32_e32 v254, s2
	s_mov_b32 s3, 0xf800000
	v_mov_b32_e32 v250, 0x260
	v_mov_b32_e32 v1, 0
	s_mov_b32 s16, 0x43180000
	s_movk_i32 s15, 0x1800
	s_mov_b32 s17, 0x83ff
	s_mov_b32 s31, 0x38e38e39
	s_movk_i32 s33, 0x200
	s_mov_b32 s39, 0x9000
	s_mov_b32 s40, 0x3e0f83e1
	s_mov_b64 s[18:19], 0xd575000
	s_mov_b32 s41, 0x41000000
	s_mov_b32 s53, 0x40400000
	s_mov_b32 s84, 0x8400
	s_mov_b32 s55, 0xc0400000
	v_mov_b32_e32 v251, 0x2000
	s_mov_b64 s[100:101], exec
	s_mov_b64 exec, -1
	s_waitcnt lgkmcnt(0)
	v_and_b32_e32 v252, 63, v242
	v_lshlrev_b32_e32 v252, 4, v252
	global_load_dwordx4 v[238:241], v252, s[10:11]
	s_waitcnt vmcnt(0)
	v_add_u32_e32 v252, 0x22800, v252
	ds_write_b128 v252, v[238:241]
	s_waitcnt lgkmcnt(0)
	s_mov_b64 exec, s[100:101]
	s_branch .LBB0_539

; template <bool DIFF, bool NOMAX>
; DI void unit(LAS unsigned char* lds, const Tensors& Tn, int b, int hd, int qb) {
;     ...
;         if (map2 == 0) {
;             float ss = 0.f;
; #pragma unroll
;             for (int dt = 0; dt < NDT; ++dt)
; #pragma unroll
;                 for (int e = 0; e < 16; ++e) { const float v = o[dt][e] * inv - Tn.lam * X[(wq2 * 128 + dt * 16 + e) * 64 + lane2]; o[dt][e] = v; ss += v * v; }
.LBB0_825:
	s_cmpk_gt_u32 s5, 0xff
	s_waitcnt vmcnt(0) lgkmcnt(0)
	s_barrier
	s_cbranch_scc1 .LBB0_827
	s_lshl_b32 s5, s4, 15
	s_add_i32 s5, s5, 0
	v_lshl_add_u32 v237, v130, 2, s5
	ds_read2st64_b32 v[130:131], v237 offset1:1
	ds_read2st64_b32 v[132:133], v237 offset0:2 offset1:3
	ds_read2st64_b32 v[198:199], v237 offset0:4 offset1:5
	ds_read2st64_b32 v[204:205], v237 offset0:6 offset1:7
	ds_read2st64_b32 v[188:189], v237 offset0:8 offset1:9
	ds_read2st64_b32 v[208:209], v237 offset0:10 offset1:11
	ds_read2st64_b32 v[182:183], v237 offset0:12 offset1:13
	ds_read2st64_b32 v[192:193], v237 offset0:14 offset1:15
	ds_read2st64_b32 v[210:211], v237 offset0:16 offset1:17
	ds_read2st64_b32 v[222:223], v237 offset0:18 offset1:19
	ds_read2st64_b32 v[134:135], v237 offset0:20 offset1:21
	ds_read2st64_b32 v[214:215], v237 offset0:22 offset1:23
	ds_read2st64_b32 v[140:141], v237 offset0:24 offset1:25
	ds_read2st64_b32 v[206:207], v237 offset0:26 offset1:27
	ds_read2st64_b32 v[138:139], v237 offset0:28 offset1:29
	ds_read2st64_b32 v[202:203], v237 offset0:30 offset1:31
	ds_read2st64_b32 v[226:227], v237 offset0:32 offset1:33
	ds_read2st64_b32 v[230:231], v237 offset0:34 offset1:35
	ds_read2st64_b32 v[136:137], v237 offset0:36 offset1:37
	ds_read2st64_b32 v[228:229], v237 offset0:38 offset1:39
	ds_read2st64_b32 v[216:217], v237 offset0:40 offset1:41
	ds_read2st64_b32 v[224:225], v237 offset0:42 offset1:43
	ds_read2st64_b32 v[156:157], v237 offset0:44 offset1:45
	ds_read2st64_b32 v[218:219], v237 offset0:46 offset1:47
	ds_read2st64_b32 v[190:191], v237 offset0:48 offset1:49
	ds_read2st64_b32 v[200:201], v237 offset0:50 offset1:51
	ds_read2st64_b32 v[184:185], v237 offset0:52 offset1:53
	ds_read2st64_b32 v[194:195], v237 offset0:54 offset1:55
	ds_read2st64_b32 v[178:179], v237 offset0:56 offset1:57
	ds_read2st64_b32 v[186:187], v237 offset0:58 offset1:59
	ds_read2st64_b32 v[176:177], v237 offset0:60 offset1:61
	ds_read2st64_b32 v[180:181], v237 offset0:62 offset1:63
	ds_read2st64_b32 v[170:171], v237 offset0:64 offset1:65
	ds_read2st64_b32 v[174:175], v237 offset0:66 offset1:67
	ds_read2st64_b32 v[166:167], v237 offset0:68 offset1:69
	ds_read2st64_b32 v[172:173], v237 offset0:70 offset1:71
	ds_read2st64_b32 v[162:163], v237 offset0:72 offset1:73
	ds_read2st64_b32 v[168:169], v237 offset0:74 offset1:75
	ds_read2st64_b32 v[160:161], v237 offset0:76 offset1:77
	ds_read2st64_b32 v[164:165], v237 offset0:78 offset1:79
	ds_read2st64_b32 v[152:153], v237 offset0:80 offset1:81
	ds_read2st64_b32 v[158:159], v237 offset0:82 offset1:83
	ds_read2st64_b32 v[148:149], v237 offset0:84 offset1:85
	ds_read2st64_b32 v[154:155], v237 offset0:86 offset1:87
	ds_read2st64_b32 v[144:145], v237 offset0:88 offset1:89
	ds_read2st64_b32 v[150:151], v237 offset0:90 offset1:91
	ds_read2st64_b32 v[142:143], v237 offset0:92 offset1:93
	ds_read2st64_b32 v[146:147], v237 offset0:94 offset1:95
	s_waitcnt lgkmcnt(14)
	v_pk_mul_f32 v[130:131], v[196:197], v[130:131]
	v_pk_mul_f32 v[132:133], v[196:197], v[132:133]
	v_pk_fma_f32 v[130:131], v[114:115], v[0:1], v[130:131] op_sel_hi:[1,0,1] neg_lo:[0,0,1] neg_hi:[0,0,1]
	v_pk_mul_f32 v[114:115], v[196:197], v[204:205]
	v_pk_fma_f32 v[116:117], v[116:117], v[0:1], v[132:133] op_sel_hi:[1,0,1] neg_lo:[0,0,1] neg_hi:[0,0,1]
	v_pk_fma_f32 v[114:115], v[120:121], v[0:1], v[114:115] op_sel_hi:[1,0,1] neg_lo:[0,0,1] neg_hi:[0,0,1]
	v_pk_mul_f32 v[120:121], v[196:197], v[198:199]
	v_and_b32_e32 v236, 31, v233
	v_pk_fma_f32 v[132:133], v[118:119], v[0:1], v[120:121] op_sel_hi:[1,0,1] neg_lo:[0,0,1] neg_hi:[0,0,1]
	v_pk_mul_f32 v[118:119], v[196:197], v[208:209]
	v_pk_mul_f32 v[120:121], v[196:197], v[188:189]
	v_pk_fma_f32 v[118:119], v[124:125], v[0:1], v[118:119] op_sel_hi:[1,0,1] neg_lo:[0,0,1] neg_hi:[0,0,1]
	v_pk_mul_f32 v[124:125], v[196:197], v[182:183]
	v_pk_fma_f32 v[122:123], v[122:123], v[0:1], v[120:121] op_sel_hi:[1,0,1] neg_lo:[0,0,1] neg_hi:[0,0,1]
	v_pk_fma_f32 v[124:125], v[126:127], v[0:1], v[124:125] op_sel_hi:[1,0,1] neg_lo:[0,0,1] neg_hi:[0,0,1]
	v_pk_mul_f32 v[126:127], v[196:197], v[222:223]
	v_pk_mul_f32 v[120:121], v[196:197], v[192:193]
	v_pk_fma_f32 v[126:127], v[100:101], v[0:1], v[126:127] op_sel_hi:[1,0,1] neg_lo:[0,0,1] neg_hi:[0,0,1]
	v_pk_mul_f32 v[100:101], v[196:197], v[210:211]
	v_pk_fma_f32 v[120:121], v[128:129], v[0:1], v[120:121] op_sel_hi:[1,0,1] neg_lo:[0,0,1] neg_hi:[0,0,1]
	v_pk_fma_f32 v[128:129], v[98:99], v[0:1], v[100:101] op_sel_hi:[1,0,1] neg_lo:[0,0,1] neg_hi:[0,0,1]
	v_pk_mul_f32 v[98:99], v[196:197], v[214:215]
	ds_read2st64_b32 v[212:213], v237 offset0:96 offset1:97
	ds_read2st64_b32 v[220:221], v237 offset0:98 offset1:99
	ds_read2st64_b32 v[204:205], v237 offset0:100 offset1:101
	ds_read2st64_b32 v[208:209], v237 offset0:102 offset1:103
	ds_read2st64_b32 v[192:193], v237 offset0:104 offset1:105
	ds_read2st64_b32 v[198:199], v237 offset0:106 offset1:107
	ds_read2st64_b32 v[182:183], v237 offset0:108 offset1:109
	ds_read2st64_b32 v[188:189], v237 offset0:110 offset1:111
	ds_read2st64_b32 v[234:235], v237 offset0:122 offset1:123
	v_pk_fma_f32 v[104:105], v[104:105], v[0:1], v[98:99] op_sel_hi:[1,0,1] neg_lo:[0,0,1] neg_hi:[0,0,1]
	v_pk_mul_f32 v[98:99], v[196:197], v[134:135]
	s_waitcnt lgkmcnt(0)
; template <int MASK> DI float shx(float v, int lane) { return __builtin_bit_cast(float, __builtin_amdgcn_ds_bpermute((lane ^ MASK) << 2, __builtin_bit_cast(int, v))); }
; template <bool DIFF, bool NOMAX>
; DI void unit(LAS unsigned char* lds, const Tensors& Tn, int b, int hd, int qb) {
;     ...
;         if (map2 == 0) {
;             float ss = 0.f;
; #pragma unroll
;             for (int dt = 0; dt < NDT; ++dt)
; #pragma unroll
;                 for (int e = 0; e < 16; ++e) { const float v = o[dt][e] * inv - Tn.lam * X[(wq2 * 128 + dt * 16 + e) * 64 + lane2]; o[dt][e] = v; ss += v * v; }
;             ss += shx<32>(ss, lane2);
	v_pk_mul_f32 v[100:101], v[196:197], v[234:235]
	v_pk_fma_f32 v[134:135], v[102:103], v[0:1], v[98:99] op_sel_hi:[1,0,1] neg_lo:[0,0,1] neg_hi:[0,0,1]
	v_pk_mul_f32 v[98:99], v[196:197], v[206:207]
	v_pk_fma_f32 v[100:101], v[12:13], v[0:1], v[100:101] op_sel_hi:[1,0,1] neg_lo:[0,0,1] neg_hi:[0,0,1]
	v_pk_fma_f32 v[102:103], v[108:109], v[0:1], v[98:99] op_sel_hi:[1,0,1] neg_lo:[0,0,1] neg_hi:[0,0,1]
	v_pk_mul_f32 v[98:99], v[196:197], v[140:141]
	s_nop 0
	v_pk_fma_f32 v[108:109], v[106:107], v[0:1], v[98:99] op_sel_hi:[1,0,1] neg_lo:[0,0,1] neg_hi:[0,0,1]
	v_pk_mul_f32 v[98:99], v[196:197], v[202:203]
	s_nop 0
	v_pk_fma_f32 v[106:107], v[112:113], v[0:1], v[98:99] op_sel_hi:[1,0,1] neg_lo:[0,0,1] neg_hi:[0,0,1]
	v_pk_mul_f32 v[98:99], v[196:197], v[138:139]
	v_pk_mul_f32 v[138:139], v[100:101], v[100:101]
	v_pk_fma_f32 v[110:111], v[110:111], v[0:1], v[98:99] op_sel_hi:[1,0,1] neg_lo:[0,0,1] neg_hi:[0,0,1]
	ds_read2st64_b32 v[214:215], v237 offset0:112 offset1:113
	ds_read2st64_b32 v[222:223], v237 offset0:114 offset1:115
	ds_read2st64_b32 v[206:207], v237 offset0:116 offset1:117
	ds_read2st64_b32 v[210:211], v237 offset0:118 offset1:119
	ds_read2st64_b32 v[98:99], v237 offset0:124 offset1:125
	ds_read2st64_b32 v[112:113], v237 offset0:126 offset1:127
	ds_read2st64_b32 v[202:203], v237 offset0:120 offset1:121
	s_waitcnt lgkmcnt(2)
	v_pk_mul_f32 v[12:13], v[196:197], v[98:99]
	s_nop 0
	v_pk_fma_f32 v[98:99], v[14:15], v[0:1], v[12:13] op_sel_hi:[1,0,1] neg_lo:[0,0,1] neg_hi:[0,0,1]
	s_waitcnt lgkmcnt(1)
	v_pk_mul_f32 v[12:13], v[196:197], v[112:113]
	v_pk_mul_f32 v[140:141], v[98:99], v[98:99]
	v_pk_fma_f32 v[16:17], v[16:17], v[0:1], v[12:13] op_sel_hi:[1,0,1] neg_lo:[0,0,1] neg_hi:[0,0,1]
	v_pk_mul_f32 v[12:13], v[196:197], v[230:231]
	s_nop 0
	v_pk_fma_f32 v[84:85], v[84:85], v[0:1], v[12:13] op_sel_hi:[1,0,1] neg_lo:[0,0,1] neg_hi:[0,0,1]
	v_pk_mul_f32 v[12:13], v[196:197], v[226:227]
	v_pk_mul_f32 v[226:227], v[130:131], v[130:131]
	v_pk_fma_f32 v[112:113], v[82:83], v[0:1], v[12:13] op_sel_hi:[1,0,1] neg_lo:[0,0,1] neg_hi:[0,0,1]
	v_pk_mul_f32 v[12:13], v[196:197], v[228:229]
	s_nop 0
	v_pk_fma_f32 v[82:83], v[88:89], v[0:1], v[12:13] op_sel_hi:[1,0,1] neg_lo:[0,0,1] neg_hi:[0,0,1]
	v_pk_mul_f32 v[12:13], v[196:197], v[136:137]
	s_nop 0
	v_pk_fma_f32 v[136:137], v[86:87], v[0:1], v[12:13] op_sel_hi:[1,0,1] neg_lo:[0,0,1] neg_hi:[0,0,1]
	v_pk_mul_f32 v[12:13], v[196:197], v[224:225]
	v_pk_mul_f32 v[224:225], v[132:133], v[132:133]
	v_pk_fma_f32 v[86:87], v[92:93], v[0:1], v[12:13] op_sel_hi:[1,0,1] neg_lo:[0,0,1] neg_hi:[0,0,1]
	v_pk_mul_f32 v[12:13], v[196:197], v[216:217]
	v_pk_mul_f32 v[216:217], v[114:115], v[114:115]
	v_pk_fma_f32 v[90:91], v[90:91], v[0:1], v[12:13] op_sel_hi:[1,0,1] neg_lo:[0,0,1] neg_hi:[0,0,1]
	v_pk_mul_f32 v[12:13], v[196:197], v[218:219]
	v_pk_mul_f32 v[218:219], v[116:117], v[116:117]
	v_pk_fma_f32 v[88:89], v[96:97], v[0:1], v[12:13] op_sel_hi:[1,0,1] neg_lo:[0,0,1] neg_hi:[0,0,1]
	v_pk_mul_f32 v[12:13], v[196:197], v[156:157]
	v_pk_mul_f32 v[156:157], v[16:17], v[16:17]
	v_pk_fma_f32 v[92:93], v[94:95], v[0:1], v[12:13] op_sel_hi:[1,0,1] neg_lo:[0,0,1] neg_hi:[0,0,1]
	v_pk_mul_f32 v[94:95], v[196:197], v[200:201]
	v_pk_mul_f32 v[200:201], v[122:123], v[122:123]
	v_pk_fma_f32 v[68:69], v[68:69], v[0:1], v[94:95] op_sel_hi:[1,0,1] neg_lo:[0,0,1] neg_hi:[0,0,1]
	v_pk_mul_f32 v[94:95], v[196:197], v[190:191]
	v_pk_mul_f32 v[190:191], v[118:119], v[118:119]
	v_pk_fma_f32 v[94:95], v[66:67], v[0:1], v[94:95] op_sel_hi:[1,0,1] neg_lo:[0,0,1] neg_hi:[0,0,1]
	v_pk_mul_f32 v[66:67], v[196:197], v[194:195]
	v_pk_mul_f32 v[194:195], v[124:125], v[124:125]
	v_pk_fma_f32 v[66:67], v[72:73], v[0:1], v[66:67] op_sel_hi:[1,0,1] neg_lo:[0,0,1] neg_hi:[0,0,1]
	v_pk_mul_f32 v[72:73], v[196:197], v[184:185]
	v_pk_mul_f32 v[184:185], v[120:121], v[120:121]
	v_pk_fma_f32 v[96:97], v[70:71], v[0:1], v[72:73] op_sel_hi:[1,0,1] neg_lo:[0,0,1] neg_hi:[0,0,1]
	v_pk_mul_f32 v[70:71], v[196:197], v[186:187]
	v_pk_mul_f32 v[72:73], v[196:197], v[178:179]
	v_pk_fma_f32 v[70:71], v[76:77], v[0:1], v[70:71] op_sel_hi:[1,0,1] neg_lo:[0,0,1] neg_hi:[0,0,1]
	v_pk_mul_f32 v[76:77], v[196:197], v[176:177]
	v_pk_fma_f32 v[74:75], v[74:75], v[0:1], v[72:73] op_sel_hi:[1,0,1] neg_lo:[0,0,1] neg_hi:[0,0,1]
	v_pk_fma_f32 v[76:77], v[78:79], v[0:1], v[76:77] op_sel_hi:[1,0,1] neg_lo:[0,0,1] neg_hi:[0,0,1]
	v_pk_mul_f32 v[78:79], v[196:197], v[174:175]
	v_pk_mul_f32 v[72:73], v[196:197], v[180:181]
	v_pk_fma_f32 v[52:53], v[52:53], v[0:1], v[78:79] op_sel_hi:[1,0,1] neg_lo:[0,0,1] neg_hi:[0,0,1]
	v_pk_mul_f32 v[78:79], v[196:197], v[170:171]
	v_pk_fma_f32 v[72:73], v[80:81], v[0:1], v[72:73] op_sel_hi:[1,0,1] neg_lo:[0,0,1] neg_hi:[0,0,1]
	v_pk_fma_f32 v[78:79], v[50:51], v[0:1], v[78:79] op_sel_hi:[1,0,1] neg_lo:[0,0,1] neg_hi:[0,0,1]
	v_pk_mul_f32 v[50:51], v[196:197], v[172:173]
	v_pk_mul_f32 v[186:187], v[128:129], v[128:129]
	v_pk_fma_f32 v[50:51], v[56:57], v[0:1], v[50:51] op_sel_hi:[1,0,1] neg_lo:[0,0,1] neg_hi:[0,0,1]
	v_pk_mul_f32 v[56:57], v[196:197], v[166:167]
	v_pk_mul_f32 v[178:179], v[126:127], v[126:127]
	v_pk_fma_f32 v[80:81], v[54:55], v[0:1], v[56:57] op_sel_hi:[1,0,1] neg_lo:[0,0,1] neg_hi:[0,0,1]
	v_pk_mul_f32 v[54:55], v[196:197], v[168:169]
	v_pk_mul_f32 v[56:57], v[196:197], v[162:163]
	v_pk_fma_f32 v[54:55], v[60:61], v[0:1], v[54:55] op_sel_hi:[1,0,1] neg_lo:[0,0,1] neg_hi:[0,0,1]
	v_pk_mul_f32 v[60:61], v[196:197], v[160:161]
	v_pk_fma_f32 v[58:59], v[58:59], v[0:1], v[56:57] op_sel_hi:[1,0,1] neg_lo:[0,0,1] neg_hi:[0,0,1]
	v_pk_fma_f32 v[60:61], v[62:63], v[0:1], v[60:61] op_sel_hi:[1,0,1] neg_lo:[0,0,1] neg_hi:[0,0,1]
; template <bool DIFF, bool NOMAX>
; DI void unit(LAS unsigned char* lds, const Tensors& Tn, int b, int hd, int qb) {
;     ...
;             for (int dt = 0; dt < NDT; ++dt)
; #pragma unroll
;                 for (int e = 0; e < 16; ++e) { const float v = o[dt][e] * inv - Tn.lam * X[(wq2 * 128 + dt * 16 + e) * 64 + lane2]; o[dt][e] = v; ss += v * v; }
	v_pk_mul_f32 v[62:63], v[196:197], v[158:159]
	v_pk_mul_f32 v[56:57], v[196:197], v[164:165]
	v_pk_fma_f32 v[36:37], v[36:37], v[0:1], v[62:63] op_sel_hi:[1,0,1] neg_lo:[0,0,1] neg_hi:[0,0,1]
	v_pk_mul_f32 v[62:63], v[196:197], v[152:153]
	v_pk_fma_f32 v[56:57], v[64:65], v[0:1], v[56:57] op_sel_hi:[1,0,1] neg_lo:[0,0,1] neg_hi:[0,0,1]
	v_pk_fma_f32 v[62:63], v[34:35], v[0:1], v[62:63] op_sel_hi:[1,0,1] neg_lo:[0,0,1] neg_hi:[0,0,1]
	v_pk_mul_f32 v[34:35], v[196:197], v[154:155]
	v_pk_mul_f32 v[180:181], v[134:135], v[134:135]
	v_pk_fma_f32 v[34:35], v[40:41], v[0:1], v[34:35] op_sel_hi:[1,0,1] neg_lo:[0,0,1] neg_hi:[0,0,1]
	v_pk_mul_f32 v[40:41], v[196:197], v[148:149]
	v_pk_mul_f32 v[176:177], v[104:105], v[104:105]
	v_pk_fma_f32 v[64:65], v[38:39], v[0:1], v[40:41] op_sel_hi:[1,0,1] neg_lo:[0,0,1] neg_hi:[0,0,1]
	v_pk_mul_f32 v[38:39], v[196:197], v[150:151]
	v_pk_mul_f32 v[40:41], v[196:197], v[144:145]
	v_pk_fma_f32 v[38:39], v[44:45], v[0:1], v[38:39] op_sel_hi:[1,0,1] neg_lo:[0,0,1] neg_hi:[0,0,1]
	v_pk_mul_f32 v[44:45], v[196:197], v[142:143]
	v_pk_fma_f32 v[42:43], v[42:43], v[0:1], v[40:41] op_sel_hi:[1,0,1] neg_lo:[0,0,1] neg_hi:[0,0,1]
	v_pk_fma_f32 v[44:45], v[46:47], v[0:1], v[44:45] op_sel_hi:[1,0,1] neg_lo:[0,0,1] neg_hi:[0,0,1]
	v_pk_mul_f32 v[46:47], v[196:197], v[220:221]
	v_pk_mul_f32 v[40:41], v[196:197], v[146:147]
	v_pk_fma_f32 v[20:21], v[20:21], v[0:1], v[46:47] op_sel_hi:[1,0,1] neg_lo:[0,0,1] neg_hi:[0,0,1]
	v_pk_mul_f32 v[46:47], v[196:197], v[212:213]
	v_pk_fma_f32 v[40:41], v[48:49], v[0:1], v[40:41] op_sel_hi:[1,0,1] neg_lo:[0,0,1] neg_hi:[0,0,1]
	v_pk_fma_f32 v[46:47], v[18:19], v[0:1], v[46:47] op_sel_hi:[1,0,1] neg_lo:[0,0,1] neg_hi:[0,0,1]
	v_pk_mul_f32 v[18:19], v[196:197], v[208:209]
	v_pk_mul_f32 v[162:163], v[108:109], v[108:109]
	v_pk_fma_f32 v[18:19], v[24:25], v[0:1], v[18:19] op_sel_hi:[1,0,1] neg_lo:[0,0,1] neg_hi:[0,0,1]
	v_pk_mul_f32 v[24:25], v[196:197], v[204:205]
	v_pk_mul_f32 v[160:161], v[102:103], v[102:103]
	v_pk_fma_f32 v[48:49], v[22:23], v[0:1], v[24:25] op_sel_hi:[1,0,1] neg_lo:[0,0,1] neg_hi:[0,0,1]
	v_pk_mul_f32 v[22:23], v[196:197], v[198:199]
	v_pk_mul_f32 v[24:25], v[196:197], v[192:193]
	v_pk_fma_f32 v[22:23], v[28:29], v[0:1], v[22:23] op_sel_hi:[1,0,1] neg_lo:[0,0,1] neg_hi:[0,0,1]
	v_pk_mul_f32 v[28:29], v[196:197], v[182:183]
	v_pk_fma_f32 v[26:27], v[26:27], v[0:1], v[24:25] op_sel_hi:[1,0,1] neg_lo:[0,0,1] neg_hi:[0,0,1]
	v_pk_fma_f32 v[28:29], v[30:31], v[0:1], v[28:29] op_sel_hi:[1,0,1] neg_lo:[0,0,1] neg_hi:[0,0,1]
	v_pk_mul_f32 v[30:31], v[196:197], v[222:223]
	v_pk_mul_f32 v[24:25], v[196:197], v[188:189]
	v_pk_fma_f32 v[4:5], v[4:5], v[0:1], v[30:31] op_sel_hi:[1,0,1] neg_lo:[0,0,1] neg_hi:[0,0,1]
	v_pk_mul_f32 v[30:31], v[196:197], v[214:215]
	v_pk_fma_f32 v[24:25], v[32:33], v[0:1], v[24:25] op_sel_hi:[1,0,1] neg_lo:[0,0,1] neg_hi:[0,0,1]
	v_pk_fma_f32 v[30:31], v[2:3], v[0:1], v[30:31] op_sel_hi:[1,0,1] neg_lo:[0,0,1] neg_hi:[0,0,1]
	v_pk_mul_f32 v[2:3], v[196:197], v[210:211]
	v_pk_mul_f32 v[166:167], v[110:111], v[110:111]
	v_pk_fma_f32 v[2:3], v[8:9], v[0:1], v[2:3] op_sel_hi:[1,0,1] neg_lo:[0,0,1] neg_hi:[0,0,1]
	v_pk_mul_f32 v[8:9], v[196:197], v[206:207]
	v_pk_mul_f32 v[164:165], v[106:107], v[106:107]
	v_pk_fma_f32 v[8:9], v[6:7], v[0:1], v[8:9] op_sel_hi:[1,0,1] neg_lo:[0,0,1] neg_hi:[0,0,1]
	s_waitcnt lgkmcnt(0)
	v_pk_mul_f32 v[6:7], v[196:197], v[202:203]
	v_pk_mul_f32 v[170:171], v[112:113], v[112:113]
	v_pk_fma_f32 v[6:7], v[10:11], v[0:1], v[6:7] op_sel_hi:[1,0,1] neg_lo:[0,0,1] neg_hi:[0,0,1]
	v_add_f32_e32 v0, v226, v227
	v_add_f32_e32 v0, v0, v218
	v_add_f32_e32 v0, v0, v219
	v_add_f32_e32 v0, v0, v224
	v_add_f32_e32 v0, v0, v225
	v_add_f32_e32 v0, v0, v216
	v_add_f32_e32 v0, v0, v217
	v_add_f32_e32 v0, v0, v200
	v_add_f32_e32 v0, v0, v201
	v_add_f32_e32 v0, v0, v190
	v_add_f32_e32 v0, v0, v191
	v_add_f32_e32 v0, v0, v194
	v_add_f32_e32 v0, v0, v195
	v_add_f32_e32 v0, v0, v184
	v_add_f32_e32 v0, v0, v185
	v_add_f32_e32 v0, v0, v186
	v_add_f32_e32 v0, v0, v187
	v_add_f32_e32 v0, v0, v178
	v_add_f32_e32 v0, v0, v179
	v_add_f32_e32 v0, v0, v180
	v_add_f32_e32 v0, v0, v181
	v_add_f32_e32 v0, v0, v176
	v_add_f32_e32 v0, v0, v177
	v_add_f32_e32 v0, v0, v162
	v_add_f32_e32 v0, v0, v163
	v_add_f32_e32 v0, v0, v160
	v_add_f32_e32 v0, v0, v161
	v_add_f32_e32 v0, v0, v166
	v_add_f32_e32 v0, v0, v167
	v_add_f32_e32 v0, v0, v164
	v_add_f32_e32 v0, v0, v165
	v_add_f32_e32 v0, v0, v170
	v_pk_mul_f32 v[168:169], v[84:85], v[84:85]
	v_add_f32_e32 v0, v0, v171
	v_add_f32_e32 v0, v0, v168
	v_pk_mul_f32 v[174:175], v[136:137], v[136:137]
	v_add_f32_e32 v0, v0, v169
	v_add_f32_e32 v0, v0, v174
	v_pk_mul_f32 v[172:173], v[82:83], v[82:83]
	v_add_f32_e32 v0, v0, v175
	v_add_f32_e32 v0, v0, v172
	v_pk_mul_f32 v[144:145], v[90:91], v[90:91]
	v_add_f32_e32 v0, v0, v173
	v_add_f32_e32 v0, v0, v144
	v_pk_mul_f32 v[142:143], v[86:87], v[86:87]
	v_add_f32_e32 v0, v0, v145
	v_add_f32_e32 v0, v0, v142
	v_pk_mul_f32 v[148:149], v[92:93], v[92:93]
	v_add_f32_e32 v0, v0, v143
	v_add_f32_e32 v0, v0, v148
	v_pk_mul_f32 v[146:147], v[88:89], v[88:89]
	v_add_f32_e32 v0, v0, v149
	v_add_f32_e32 v0, v0, v146
	v_pk_mul_f32 v[152:153], v[94:95], v[94:95]
	v_add_f32_e32 v0, v0, v147
	v_add_f32_e32 v0, v0, v152
	v_pk_mul_f32 v[150:151], v[68:69], v[68:69]
	v_add_f32_e32 v0, v0, v153
	v_add_f32_e32 v0, v0, v150
	v_pk_mul_f32 v[158:159], v[96:97], v[96:97]
	v_add_f32_e32 v0, v0, v151
	v_add_f32_e32 v0, v0, v158
	v_pk_mul_f32 v[154:155], v[66:67], v[66:67]
	v_add_f32_e32 v0, v0, v159
	v_add_f32_e32 v0, v0, v154
	v_pk_mul_f32 v[182:183], v[74:75], v[74:75]
	v_add_f32_e32 v0, v0, v155
; DI unsigned cvtpk(float lo, float hi) { f32x2_t v = {lo, hi}; bf16x2_t b = __builtin_convertvector(v, bf16x2_t); return __builtin_bit_cast(unsigned, b); }
; template <int MASK> DI float shx(float v, int lane) { return __builtin_bit_cast(float, __builtin_amdgcn_ds_bpermute((lane ^ MASK) << 2, __builtin_bit_cast(int, v))); }
; template <bool DIFF, bool NOMAX>
; DI void unit(LAS unsigned char* lds, const Tensors& Tn, int b, int hd, int qb) {
;     ...
;                 for (int e = 0; e < 16; ++e) { const float v = o[dt][e] * inv - Tn.lam * X[(wq2 * 128 + dt * 16 + e) * 64 + lane2]; o[dt][e] = v; ss += v * v; }
;             ss += shx<32>(ss, lane2);
;             const float rs = __builtin_amdgcn_rsqf(ss * (1.0f / 256.0f) + EPS) * (1.0f - LAMBDA_INIT);
;             bf16_t* yp = Tn.Y + (tok0 + q02 + r2) * 2048 + hd * 256 + 4 * h2;
; #pragma unroll
;             for (int dt = 0; dt < NDT; ++dt)
; #pragma unroll
;                 for (int g = 0; g < 4; ++g) { const f32x4 gg = *(const f32x4*)(Tn.sub_g + 32 * dt + 8 * g + 4 * h2);
;                     u32x2 pk; pk.x = cvtpk(o[dt][4 * g] * rs * gg[0], o[dt][4 * g + 1] * rs * gg[1]); pk.y = cvtpk(o[dt][4 * g + 2] * rs * gg[2], o[dt][4 * g + 3] * rs * gg[3]);
;                     *(u32x2*)(yp + 32 * dt + 8 * g) = pk; }
	v_add_f32_e32 v0, v0, v182
	v_lshl_or_b32 v12, s4, 5, v236
	v_pk_mul_f32 v[32:33], v[70:71], v[70:71]
	v_add_f32_e32 v0, v0, v183
	v_or_b32_e32 v229, s85, v12
	v_lshrrev_b32_e32 v12, 3, v233
	v_add_f32_e32 v0, v0, v32
	v_and_b32_e32 v233, 4, v12
	v_pk_mul_f32 v[192:193], v[76:77], v[76:77]
	v_add_f32_e32 v0, v0, v33
	v_lshlrev_b32_e32 v228, 2, v233
	v_add_u32_e32 v253, 0x22800, v228
	v_add_f32_e32 v0, v0, v192
	ds_read_b128 v[12:15], v253
	v_pk_mul_f32 v[188:189], v[72:73], v[72:73]
	v_add_f32_e32 v0, v0, v193
	v_add_f32_e32 v0, v0, v188
	v_pk_mul_f32 v[204:205], v[78:79], v[78:79]
	v_add_f32_e32 v0, v0, v189
	v_add_f32_e32 v0, v0, v204
	v_pk_mul_f32 v[198:199], v[52:53], v[52:53]
	v_add_f32_e32 v0, v0, v205
	v_add_f32_e32 v0, v0, v198
	v_pk_mul_f32 v[212:213], v[80:81], v[80:81]
	v_add_f32_e32 v0, v0, v199
	v_add_f32_e32 v0, v0, v212
	v_pk_mul_f32 v[208:209], v[50:51], v[50:51]
	v_add_f32_e32 v0, v0, v213
	v_add_f32_e32 v0, v0, v208
	v_pk_mul_f32 v[202:203], v[58:59], v[58:59]
	v_add_f32_e32 v0, v0, v209
	v_add_f32_e32 v0, v0, v202
	v_pk_mul_f32 v[10:11], v[54:55], v[54:55]
	v_add_f32_e32 v0, v0, v203
	v_add_f32_e32 v0, v0, v10
	v_pk_mul_f32 v[210:211], v[60:61], v[60:61]
	v_add_f32_e32 v0, v0, v11
	v_add_f32_e32 v0, v0, v210
	v_pk_mul_f32 v[206:207], v[56:57], v[56:57]
	v_add_f32_e32 v0, v0, v211
	v_add_f32_e32 v0, v0, v206
	v_pk_mul_f32 v[220:221], v[62:63], v[62:63]
	v_add_f32_e32 v0, v0, v207
	v_add_f32_e32 v0, v0, v220
	v_pk_mul_f32 v[214:215], v[36:37], v[36:37]
	v_add_f32_e32 v0, v0, v221
	v_add_f32_e32 v0, v0, v214
	v_pk_mul_f32 v[230:231], v[64:65], v[64:65]
	v_add_f32_e32 v0, v0, v215
	v_add_f32_e32 v0, v0, v230
	v_pk_mul_f32 v[222:223], v[34:35], v[34:35]
	v_add_f32_e32 v0, v0, v231
	v_add_f32_e32 v0, v0, v222
	v_pk_mul_f32 v[226:227], v[42:43], v[42:43]
	v_add_f32_e32 v0, v0, v223
	v_add_f32_e32 v0, v0, v226
	v_pk_mul_f32 v[234:235], v[38:39], v[38:39]
	v_add_f32_e32 v0, v0, v227
	v_add_f32_e32 v0, v0, v234
	v_pk_mul_f32 v[224:225], v[44:45], v[44:45]
	v_add_f32_e32 v0, v0, v235
	v_add_f32_e32 v0, v0, v224
	v_pk_mul_f32 v[218:219], v[40:41], v[40:41]
	v_add_f32_e32 v0, v0, v225
	v_add_f32_e32 v0, v0, v218
	v_pk_mul_f32 v[200:201], v[46:47], v[46:47]
	v_add_f32_e32 v0, v0, v219
	v_add_f32_e32 v0, v0, v200
	v_pk_mul_f32 v[216:217], v[20:21], v[20:21]
	v_add_f32_e32 v0, v0, v201
	v_add_f32_e32 v0, v0, v216
	v_pk_mul_f32 v[194:195], v[48:49], v[48:49]
	v_add_f32_e32 v0, v0, v217
	v_add_f32_e32 v0, v0, v194
	v_pk_mul_f32 v[190:191], v[18:19], v[18:19]
	v_add_f32_e32 v0, v0, v195
	v_add_f32_e32 v0, v0, v190
	v_pk_mul_f32 v[186:187], v[26:27], v[26:27]
	v_add_f32_e32 v0, v0, v191
	v_add_f32_e32 v0, v0, v186
	v_pk_mul_f32 v[184:185], v[22:23], v[22:23]
	v_add_f32_e32 v0, v0, v187
	v_add_f32_e32 v0, v0, v184
	v_pk_mul_f32 v[180:181], v[28:29], v[28:29]
	v_add_f32_e32 v0, v0, v185
	v_add_f32_e32 v0, v0, v180
	v_pk_mul_f32 v[178:179], v[24:25], v[24:25]
	v_add_f32_e32 v0, v0, v181
	v_add_f32_e32 v0, v0, v178
	v_pk_mul_f32 v[162:163], v[30:31], v[30:31]
	v_add_f32_e32 v0, v0, v179
	v_add_f32_e32 v0, v0, v162
	v_pk_mul_f32 v[176:177], v[4:5], v[4:5]
	v_add_f32_e32 v0, v0, v163
	v_add_f32_e32 v0, v0, v176
	v_pk_mul_f32 v[166:167], v[8:9], v[8:9]
	v_add_f32_e32 v0, v0, v177
	v_add_f32_e32 v0, v0, v166
	v_pk_mul_f32 v[160:161], v[2:3], v[2:3]
	v_add_f32_e32 v0, v0, v167
	v_add_f32_e32 v0, v0, v160
	v_pk_mul_f32 v[164:165], v[6:7], v[6:7]
	v_add_f32_e32 v0, v0, v161
	v_add_f32_e32 v0, v0, v164
	v_add_f32_e32 v0, v0, v165
	v_add_f32_e32 v0, v0, v138
	v_add_f32_e32 v0, v0, v139
	v_add_f32_e32 v0, v0, v140
	v_add_f32_e32 v0, v0, v141
	v_add_f32_e32 v0, v0, v156
	v_add_f32_e32 v32, v0, v157
	ds_bpermute_b32 v33, v232, v32
	v_or_b32_e32 v0, s8, v229
	v_readlane_b32 s4, v255, 10
	v_lshlrev_b32_e32 v0, 12, v0
	v_readlane_b32 s5, v255, 11
	s_lshl_b32 s8, s78, 1
	s_nop 0
	v_lshl_add_u64 v[10:11], s[4:5], 0, v[0:1]
	s_waitcnt lgkmcnt(0)
	v_add_f32_e32 v0, v32, v33
	v_mov_b32_e32 v32, 0x358637bd
	v_fmamk_f32 v0, v0, 0x3b800000, v32
	v_rsq_f32_e32 v32, v0
	v_lshl_add_u64 v[10:11], v[10:11], 0, s[8:9]
	v_lshlrev_b32_e32 v0, 1, v233
	v_lshl_add_u64 v[10:11], v[10:11], 0, v[0:1]
	v_mul_f32_e32 v0, 0x3f4ccccd, v32
	v_pk_mul_f32 v[32:33], v[130:131], v[0:1] op_sel_hi:[1,0]
	v_pk_mul_f32 v[104:105], v[104:105], v[0:1] op_sel_hi:[1,0]
	s_waitcnt lgkmcnt(0)
	v_pk_mul_f32 v[12:13], v[12:13], v[32:33]
	v_pk_mul_f32 v[32:33], v[116:117], v[0:1] op_sel_hi:[1,0]
	v_cvt_pk_bf16_f32 v12, v12, v13
	v_pk_mul_f32 v[14:15], v[14:15], v[32:33]
	v_pk_mul_f32 v[32:33], v[132:133], v[0:1] op_sel_hi:[1,0]
	v_cvt_pk_bf16_f32 v13, v14, v15
	global_store_dwordx2 v[10:11], v[12:13], off
	ds_read_b128 v[12:15], v253 offset:32
	v_pk_mul_f32 v[102:103], v[102:103], v[0:1] op_sel_hi:[1,0]
	v_pk_mul_f32 v[84:85], v[84:85], v[0:1] op_sel_hi:[1,0]
	v_pk_mul_f32 v[82:83], v[82:83], v[0:1] op_sel_hi:[1,0]
	v_pk_mul_f32 v[68:69], v[68:69], v[0:1] op_sel_hi:[1,0]
	v_pk_mul_f32 v[66:67], v[66:67], v[0:1] op_sel_hi:[1,0]
	v_pk_mul_f32 v[52:53], v[52:53], v[0:1] op_sel_hi:[1,0]
	v_pk_mul_f32 v[50:51], v[50:51], v[0:1] op_sel_hi:[1,0]
	v_pk_mul_f32 v[36:37], v[36:37], v[0:1] op_sel_hi:[1,0]
	v_pk_mul_f32 v[34:35], v[34:35], v[0:1] op_sel_hi:[1,0]
	v_pk_mul_f32 v[20:21], v[20:21], v[0:1] op_sel_hi:[1,0]
	v_pk_mul_f32 v[18:19], v[18:19], v[0:1] op_sel_hi:[1,0]
	v_pk_mul_f32 v[4:5], v[4:5], v[0:1] op_sel_hi:[1,0]
	v_pk_mul_f32 v[2:3], v[2:3], v[0:1] op_sel_hi:[1,0]
	v_pk_mul_f32 v[6:7], v[6:7], v[0:1] op_sel_hi:[1,0]
	s_waitcnt lgkmcnt(0)
; DI unsigned cvtpk(float lo, float hi) { f32x2_t v = {lo, hi}; bf16x2_t b = __builtin_convertvector(v, bf16x2_t); return __builtin_bit_cast(unsigned, b); }
; template <bool DIFF, bool NOMAX>
; DI void unit(LAS unsigned char* lds, const Tensors& Tn, int b, int hd, int qb) {
;     ...
;             for (int dt = 0; dt < NDT; ++dt)
; #pragma unroll
;                 for (int g = 0; g < 4; ++g) { const f32x4 gg = *(const f32x4*)(Tn.sub_g + 32 * dt + 8 * g + 4 * h2);
;                     u32x2 pk; pk.x = cvtpk(o[dt][4 * g] * rs * gg[0], o[dt][4 * g + 1] * rs * gg[1]); pk.y = cvtpk(o[dt][4 * g + 2] * rs * gg[2], o[dt][4 * g + 3] * rs * gg[3]);
;                     *(u32x2*)(yp + 32 * dt + 8 * g) = pk; }
	v_pk_mul_f32 v[12:13], v[12:13], v[32:33]
	v_pk_mul_f32 v[32:33], v[114:115], v[0:1] op_sel_hi:[1,0]
	v_cvt_pk_bf16_f32 v12, v12, v13
	v_pk_mul_f32 v[14:15], v[14:15], v[32:33]
	v_pk_mul_f32 v[32:33], v[122:123], v[0:1] op_sel_hi:[1,0]
	v_cvt_pk_bf16_f32 v13, v14, v15
	global_store_dwordx2 v[10:11], v[12:13], off offset:16
	ds_read_b128 v[12:15], v253 offset:64
	v_pk_mul_f32 v[114:115], v[126:127], v[0:1] op_sel_hi:[1,0]
	s_waitcnt lgkmcnt(0)
	v_pk_mul_f32 v[12:13], v[12:13], v[32:33]
	v_pk_mul_f32 v[32:33], v[118:119], v[0:1] op_sel_hi:[1,0]
	v_cvt_pk_bf16_f32 v12, v12, v13
	v_pk_mul_f32 v[14:15], v[14:15], v[32:33]
	v_pk_mul_f32 v[32:33], v[124:125], v[0:1] op_sel_hi:[1,0]
	v_cvt_pk_bf16_f32 v13, v14, v15
	global_store_dwordx2 v[10:11], v[12:13], off offset:32
	ds_read_b128 v[12:15], v253 offset:96
	s_waitcnt lgkmcnt(0)
	v_pk_mul_f32 v[12:13], v[12:13], v[32:33]
	v_pk_mul_f32 v[32:33], v[120:121], v[0:1] op_sel_hi:[1,0]
	v_cvt_pk_bf16_f32 v12, v12, v13
	v_pk_mul_f32 v[14:15], v[14:15], v[32:33]
	v_pk_mul_f32 v[32:33], v[128:129], v[0:1] op_sel_hi:[1,0]
	v_cvt_pk_bf16_f32 v13, v14, v15
	global_store_dwordx2 v[10:11], v[12:13], off offset:48
	ds_read_b128 v[12:15], v253 offset:128
	s_waitcnt lgkmcnt(0)
	v_pk_mul_f32 v[12:13], v[32:33], v[12:13]
	v_pk_mul_f32 v[14:15], v[114:115], v[14:15]
	v_cvt_pk_bf16_f32 v12, v12, v13
	v_cvt_pk_bf16_f32 v13, v14, v15
	global_store_dwordx2 v[10:11], v[12:13], off offset:64
	ds_read_b128 v[12:15], v253 offset:160
	v_pk_mul_f32 v[32:33], v[134:135], v[0:1] op_sel_hi:[1,0]
	s_waitcnt lgkmcnt(0)
	v_pk_mul_f32 v[14:15], v[104:105], v[14:15]
	v_pk_mul_f32 v[12:13], v[32:33], v[12:13]
	v_pk_mul_f32 v[32:33], v[108:109], v[0:1] op_sel_hi:[1,0]
	v_cvt_pk_bf16_f32 v12, v12, v13
	v_cvt_pk_bf16_f32 v13, v14, v15
	global_store_dwordx2 v[10:11], v[12:13], off offset:80
	ds_read_b128 v[12:15], v253 offset:192
	s_waitcnt lgkmcnt(0)
	v_pk_mul_f32 v[12:13], v[32:33], v[12:13]
	v_pk_mul_f32 v[14:15], v[102:103], v[14:15]
	v_cvt_pk_bf16_f32 v12, v12, v13
	v_cvt_pk_bf16_f32 v13, v14, v15
	global_store_dwordx2 v[10:11], v[12:13], off offset:96
	ds_read_b128 v[12:15], v253 offset:224
	v_pk_mul_f32 v[32:33], v[110:111], v[0:1] op_sel_hi:[1,0]
	v_pk_mul_f32 v[102:103], v[106:107], v[0:1] op_sel_hi:[1,0]
	s_waitcnt lgkmcnt(0)
	v_pk_mul_f32 v[12:13], v[32:33], v[12:13]
	v_pk_mul_f32 v[14:15], v[102:103], v[14:15]
	v_cvt_pk_bf16_f32 v12, v12, v13
	v_cvt_pk_bf16_f32 v13, v14, v15
	global_store_dwordx2 v[10:11], v[12:13], off offset:112
	ds_read_b128 v[12:15], v253 offset:256
	v_pk_mul_f32 v[32:33], v[112:113], v[0:1] op_sel_hi:[1,0]
	s_waitcnt lgkmcnt(0)
	v_pk_mul_f32 v[14:15], v[84:85], v[14:15]
	v_pk_mul_f32 v[12:13], v[32:33], v[12:13]
	v_pk_mul_f32 v[32:33], v[136:137], v[0:1] op_sel_hi:[1,0]
	v_cvt_pk_bf16_f32 v12, v12, v13
	v_cvt_pk_bf16_f32 v13, v14, v15
	global_store_dwordx2 v[10:11], v[12:13], off offset:128
	ds_read_b128 v[12:15], v253 offset:288
	s_waitcnt lgkmcnt(0)
	v_pk_mul_f32 v[12:13], v[32:33], v[12:13]
	v_pk_mul_f32 v[14:15], v[82:83], v[14:15]
	v_cvt_pk_bf16_f32 v12, v12, v13
	v_cvt_pk_bf16_f32 v13, v14, v15
	global_store_dwordx2 v[10:11], v[12:13], off offset:144
	ds_read_b128 v[12:15], v253 offset:320
	v_pk_mul_f32 v[32:33], v[90:91], v[0:1] op_sel_hi:[1,0]
	v_pk_mul_f32 v[82:83], v[86:87], v[0:1] op_sel_hi:[1,0]
	s_waitcnt lgkmcnt(0)
	v_pk_mul_f32 v[12:13], v[32:33], v[12:13]
	v_pk_mul_f32 v[14:15], v[82:83], v[14:15]
	v_cvt_pk_bf16_f32 v12, v12, v13
	v_cvt_pk_bf16_f32 v13, v14, v15
	global_store_dwordx2 v[10:11], v[12:13], off offset:160
	ds_read_b128 v[12:15], v253 offset:352
	v_pk_mul_f32 v[32:33], v[92:93], v[0:1] op_sel_hi:[1,0]
	v_pk_mul_f32 v[82:83], v[88:89], v[0:1] op_sel_hi:[1,0]
	s_waitcnt lgkmcnt(0)
	v_pk_mul_f32 v[12:13], v[32:33], v[12:13]
	v_pk_mul_f32 v[14:15], v[82:83], v[14:15]
	v_cvt_pk_bf16_f32 v12, v12, v13
	v_cvt_pk_bf16_f32 v13, v14, v15
	global_store_dwordx2 v[10:11], v[12:13], off offset:176
	ds_read_b128 v[12:15], v253 offset:384
	v_pk_mul_f32 v[32:33], v[94:95], v[0:1] op_sel_hi:[1,0]
	s_waitcnt lgkmcnt(0)
	v_pk_mul_f32 v[14:15], v[68:69], v[14:15]
	v_pk_mul_f32 v[12:13], v[32:33], v[12:13]
	v_pk_mul_f32 v[32:33], v[96:97], v[0:1] op_sel_hi:[1,0]
	v_cvt_pk_bf16_f32 v12, v12, v13
	v_cvt_pk_bf16_f32 v13, v14, v15
	global_store_dwordx2 v[10:11], v[12:13], off offset:192
	ds_read_b128 v[12:15], v253 offset:416
	s_waitcnt lgkmcnt(0)
	v_pk_mul_f32 v[12:13], v[32:33], v[12:13]
	v_pk_mul_f32 v[14:15], v[66:67], v[14:15]
	v_cvt_pk_bf16_f32 v12, v12, v13
	v_cvt_pk_bf16_f32 v13, v14, v15
	global_store_dwordx2 v[10:11], v[12:13], off offset:208
	ds_read_b128 v[12:15], v253 offset:448
	v_pk_mul_f32 v[32:33], v[74:75], v[0:1] op_sel_hi:[1,0]
	v_pk_mul_f32 v[66:67], v[70:71], v[0:1] op_sel_hi:[1,0]
	s_waitcnt lgkmcnt(0)
	v_pk_mul_f32 v[12:13], v[32:33], v[12:13]
	v_pk_mul_f32 v[14:15], v[66:67], v[14:15]
	v_cvt_pk_bf16_f32 v12, v12, v13
	v_cvt_pk_bf16_f32 v13, v14, v15
	global_store_dwordx2 v[10:11], v[12:13], off offset:224
	ds_read_b128 v[12:15], v253 offset:480
	v_pk_mul_f32 v[32:33], v[76:77], v[0:1] op_sel_hi:[1,0]
	v_pk_mul_f32 v[66:67], v[72:73], v[0:1] op_sel_hi:[1,0]
	s_waitcnt lgkmcnt(0)
	v_pk_mul_f32 v[12:13], v[32:33], v[12:13]
	v_pk_mul_f32 v[14:15], v[66:67], v[14:15]
	v_cvt_pk_bf16_f32 v12, v12, v13
	v_cvt_pk_bf16_f32 v13, v14, v15
	global_store_dwordx2 v[10:11], v[12:13], off offset:240
	ds_read_b128 v[12:15], v253 offset:512
	v_pk_mul_f32 v[32:33], v[78:79], v[0:1] op_sel_hi:[1,0]
	s_waitcnt lgkmcnt(0)
; DI unsigned cvtpk(float lo, float hi) { f32x2_t v = {lo, hi}; bf16x2_t b = __builtin_convertvector(v, bf16x2_t); return __builtin_bit_cast(unsigned, b); }
; template <bool DIFF, bool NOMAX>
; DI void unit(LAS unsigned char* lds, const Tensors& Tn, int b, int hd, int qb) {
;     ...
;             for (int dt = 0; dt < NDT; ++dt)
; #pragma unroll
;                 for (int g = 0; g < 4; ++g) { const f32x4 gg = *(const f32x4*)(Tn.sub_g + 32 * dt + 8 * g + 4 * h2);
;                     u32x2 pk; pk.x = cvtpk(o[dt][4 * g] * rs * gg[0], o[dt][4 * g + 1] * rs * gg[1]); pk.y = cvtpk(o[dt][4 * g + 2] * rs * gg[2], o[dt][4 * g + 3] * rs * gg[3]);
;                     *(u32x2*)(yp + 32 * dt + 8 * g) = pk; }
	v_pk_mul_f32 v[14:15], v[52:53], v[14:15]
	v_pk_mul_f32 v[12:13], v[32:33], v[12:13]
	v_pk_mul_f32 v[32:33], v[80:81], v[0:1] op_sel_hi:[1,0]
	v_cvt_pk_bf16_f32 v12, v12, v13
	v_cvt_pk_bf16_f32 v13, v14, v15
	global_store_dwordx2 v[10:11], v[12:13], off offset:256
	ds_read_b128 v[12:15], v253 offset:544
	s_waitcnt lgkmcnt(0)
	v_pk_mul_f32 v[12:13], v[32:33], v[12:13]
	v_pk_mul_f32 v[14:15], v[50:51], v[14:15]
	v_cvt_pk_bf16_f32 v12, v12, v13
	v_cvt_pk_bf16_f32 v13, v14, v15
	global_store_dwordx2 v[10:11], v[12:13], off offset:272
	ds_read_b128 v[12:15], v253 offset:576
	v_pk_mul_f32 v[32:33], v[58:59], v[0:1] op_sel_hi:[1,0]
	v_pk_mul_f32 v[50:51], v[54:55], v[0:1] op_sel_hi:[1,0]
	s_waitcnt lgkmcnt(0)
	v_pk_mul_f32 v[12:13], v[32:33], v[12:13]
	v_pk_mul_f32 v[14:15], v[50:51], v[14:15]
	v_cvt_pk_bf16_f32 v12, v12, v13
	v_cvt_pk_bf16_f32 v13, v14, v15
	global_store_dwordx2 v[10:11], v[12:13], off offset:288
	ds_read_b128 v[12:15], v253 offset:608
	v_pk_mul_f32 v[32:33], v[60:61], v[0:1] op_sel_hi:[1,0]
	v_pk_mul_f32 v[50:51], v[56:57], v[0:1] op_sel_hi:[1,0]
	s_waitcnt lgkmcnt(0)
	v_pk_mul_f32 v[12:13], v[32:33], v[12:13]
	v_pk_mul_f32 v[14:15], v[50:51], v[14:15]
	v_cvt_pk_bf16_f32 v12, v12, v13
	v_cvt_pk_bf16_f32 v13, v14, v15
	global_store_dwordx2 v[10:11], v[12:13], off offset:304
	ds_read_b128 v[12:15], v253 offset:640
	v_pk_mul_f32 v[32:33], v[62:63], v[0:1] op_sel_hi:[1,0]
	s_waitcnt lgkmcnt(0)
	v_pk_mul_f32 v[14:15], v[36:37], v[14:15]
	v_pk_mul_f32 v[12:13], v[32:33], v[12:13]
	v_pk_mul_f32 v[32:33], v[64:65], v[0:1] op_sel_hi:[1,0]
	v_cvt_pk_bf16_f32 v12, v12, v13
	v_cvt_pk_bf16_f32 v13, v14, v15
	global_store_dwordx2 v[10:11], v[12:13], off offset:320
	ds_read_b128 v[12:15], v253 offset:672
	s_waitcnt lgkmcnt(0)
	v_pk_mul_f32 v[12:13], v[32:33], v[12:13]
	v_pk_mul_f32 v[14:15], v[34:35], v[14:15]
	v_cvt_pk_bf16_f32 v12, v12, v13
	v_cvt_pk_bf16_f32 v13, v14, v15
	global_store_dwordx2 v[10:11], v[12:13], off offset:336
	ds_read_b128 v[12:15], v253 offset:704
	v_pk_mul_f32 v[32:33], v[42:43], v[0:1] op_sel_hi:[1,0]
	v_pk_mul_f32 v[34:35], v[38:39], v[0:1] op_sel_hi:[1,0]
	s_waitcnt lgkmcnt(0)
	v_pk_mul_f32 v[12:13], v[32:33], v[12:13]
	v_pk_mul_f32 v[14:15], v[34:35], v[14:15]
	v_cvt_pk_bf16_f32 v12, v12, v13
	v_cvt_pk_bf16_f32 v13, v14, v15
	global_store_dwordx2 v[10:11], v[12:13], off offset:352
	ds_read_b128 v[12:15], v253 offset:736
	v_pk_mul_f32 v[32:33], v[44:45], v[0:1] op_sel_hi:[1,0]
	v_pk_mul_f32 v[34:35], v[40:41], v[0:1] op_sel_hi:[1,0]
	s_waitcnt lgkmcnt(0)
	v_pk_mul_f32 v[12:13], v[32:33], v[12:13]
	v_pk_mul_f32 v[14:15], v[34:35], v[14:15]
	v_cvt_pk_bf16_f32 v12, v12, v13
	v_cvt_pk_bf16_f32 v13, v14, v15
	global_store_dwordx2 v[10:11], v[12:13], off offset:368
	ds_read_b128 v[12:15], v253 offset:768
	v_pk_mul_f32 v[32:33], v[46:47], v[0:1] op_sel_hi:[1,0]
	s_waitcnt lgkmcnt(0)
	v_pk_mul_f32 v[14:15], v[20:21], v[14:15]
	v_pk_mul_f32 v[12:13], v[32:33], v[12:13]
	v_pk_mul_f32 v[20:21], v[48:49], v[0:1] op_sel_hi:[1,0]
	v_cvt_pk_bf16_f32 v12, v12, v13
	v_cvt_pk_bf16_f32 v13, v14, v15
	global_store_dwordx2 v[10:11], v[12:13], off offset:384
	ds_read_b128 v[12:15], v253 offset:800
	s_waitcnt lgkmcnt(0)
	v_pk_mul_f32 v[12:13], v[20:21], v[12:13]
	v_pk_mul_f32 v[14:15], v[18:19], v[14:15]
	v_cvt_pk_bf16_f32 v12, v12, v13
	v_cvt_pk_bf16_f32 v13, v14, v15
	global_store_dwordx2 v[10:11], v[12:13], off offset:400
	ds_read_b128 v[12:15], v253 offset:832
	v_pk_mul_f32 v[18:19], v[26:27], v[0:1] op_sel_hi:[1,0]
	v_pk_mul_f32 v[20:21], v[22:23], v[0:1] op_sel_hi:[1,0]
	s_waitcnt lgkmcnt(0)
	v_pk_mul_f32 v[12:13], v[18:19], v[12:13]
	v_pk_mul_f32 v[14:15], v[20:21], v[14:15]
	v_cvt_pk_bf16_f32 v12, v12, v13
	v_cvt_pk_bf16_f32 v13, v14, v15
	global_store_dwordx2 v[10:11], v[12:13], off offset:416
	ds_read_b128 v[12:15], v253 offset:864
	v_pk_mul_f32 v[18:19], v[28:29], v[0:1] op_sel_hi:[1,0]
	v_pk_mul_f32 v[20:21], v[24:25], v[0:1] op_sel_hi:[1,0]
	s_waitcnt lgkmcnt(0)
	v_pk_mul_f32 v[12:13], v[18:19], v[12:13]
	v_pk_mul_f32 v[14:15], v[20:21], v[14:15]
	v_cvt_pk_bf16_f32 v12, v12, v13
	v_cvt_pk_bf16_f32 v13, v14, v15
	global_store_dwordx2 v[10:11], v[12:13], off offset:432
	ds_read_b128 v[12:15], v253 offset:896
	v_pk_mul_f32 v[18:19], v[30:31], v[0:1] op_sel_hi:[1,0]
	s_waitcnt lgkmcnt(0)
	v_pk_mul_f32 v[4:5], v[4:5], v[14:15]
	v_pk_mul_f32 v[12:13], v[18:19], v[12:13]
	s_nop 0
	v_cvt_pk_bf16_f32 v12, v12, v13
	v_cvt_pk_bf16_f32 v13, v4, v5
	global_store_dwordx2 v[10:11], v[12:13], off offset:448
	ds_read_b128 v[12:15], v253 offset:928
	v_pk_mul_f32 v[4:5], v[8:9], v[0:1] op_sel_hi:[1,0]
	v_pk_mul_f32 v[8:9], v[100:101], v[0:1] op_sel_hi:[1,0]
	s_waitcnt lgkmcnt(0)
	v_pk_mul_f32 v[4:5], v[4:5], v[12:13]
	v_pk_mul_f32 v[2:3], v[2:3], v[14:15]
	v_cvt_pk_bf16_f32 v4, v4, v5
	v_cvt_pk_bf16_f32 v5, v2, v3
	global_store_dwordx2 v[10:11], v[4:5], off offset:464
	ds_read_b128 v[2:5], v253 offset:960
	s_waitcnt lgkmcnt(0)
	v_pk_mul_f32 v[2:3], v[6:7], v[2:3]
	v_pk_mul_f32 v[4:5], v[8:9], v[4:5]
	v_cvt_pk_bf16_f32 v2, v2, v3
	v_cvt_pk_bf16_f32 v3, v4, v5
	global_store_dwordx2 v[10:11], v[2:3], off offset:480
	ds_read_b128 v[2:5], v253 offset:992
	v_pk_mul_f32 v[6:7], v[98:99], v[0:1] op_sel_hi:[1,0]
	v_pk_mul_f32 v[8:9], v[16:17], v[0:1] op_sel_hi:[1,0]
	s_waitcnt lgkmcnt(0)
	v_pk_mul_f32 v[2:3], v[6:7], v[2:3]
	v_pk_mul_f32 v[4:5], v[8:9], v[4:5]
	v_cvt_pk_bf16_f32 v2, v2, v3
	v_cvt_pk_bf16_f32 v3, v4, v5
	global_store_dwordx2 v[10:11], v[2:3], off offset:496
